# v19 + w_out1/w_gate1 transposes by arrival rank at the end of the layer-1 in-proj (one atomic per WG, static contiguous range 6/5/5/4/4/3/3/2 tiles) instead of 2-tile tickets
# speedup vs baseline: 1.0082x; 1.0025x over previous
; __global__ void __launch_bounds__(NTHREADS, 2) mk_fwd(Params P) {
;     ...
;     if (IN(7)) {
;         transpose_convert(lds, P.w_out + (size_t)2048 * 2048, WOUT1, 2048, 2048, G, bid);
;         transpose_convert(lds, P.w_gate + (size_t)2048 * 2048, WG1, 2048, 2048, G, bid);
;     }
.LBB0_570:
	s_waitcnt vmcnt(0)
	s_barrier
	v_writelane_b32 v254, s16, 8
	v_writelane_b32 v254, s17, 9
	s_add_u32 s24, s40, 0x2000000
	s_addc_u32 s25, s41, 0
	s_add_u32 s22, s40, 0x2800000
	s_addc_u32 s23, s41, 0
	s_movk_i32 s98, 1
	v_mov_b32_e32 v46, 0x20008
	s_add_u32 s10, s54, 0xa000
	s_addc_u32 s11, s55, 0
	s_and_saveexec_b64 s[18:19], s[12:13]
	s_cbranch_execz .Ldyn7_nofirst
	s_and_b32 s99, s2, 7
	s_lshl_b32 s99, s99, 6
	s_add_i32 s99, s99, 0x8000
	v_mov_b32_e32 v250, s99
	v_mov_b32_e32 v252, 1
	v_mov_b32_e32 v253, 0x2000c
	ds_read_b32 v254, v253
	s_waitcnt lgkmcnt(0)
	v_readfirstlane_b32 s99, v254
	s_cmp_eq_u32 s99, 1
	s_cbranch_scc1 .Lgg6_f
	buffer_wbl2 sc1
	s_waitcnt vmcnt(0)

; #define LAS __attribute__((address_space(3)))
; template <bool REMAP = false>
; __device__ __forceinline__ void transpose_convert(LAS unsigned char* lds, const float* src, bf16_t* dst, int K, int N, int G, int bid) {
;     LAS float* tile = (LAS float*)lds;
;     const int tid = threadIdx.x, ntn = N / 64, ntiles = (K / 128) * ntn;
;     const int r0 = tid >> 4, c4 = tid & 15;
;     f32x4 v[4];
;     if (bid < ntiles) { const int k0 = (bid / ntn) * 128, n0 = (bid % ntn) * 64;
; #pragma unroll
;         for (int i = 0; i < 4; ++i) v[i] = __builtin_nontemporal_load((const f32x4*)(src + (size_t)(k0 + r0 + 32 * i) * N + n0 + c4 * 4)); }
; __global__ void __launch_bounds__(NTHREADS, 2) mk_fwd(Params P) {
;     ...
;     if (IN(7)) {
;         transpose_convert(lds, P.w_out + (size_t)2048 * 2048, WOUT1, 2048, 2048, G, bid);
;         transpose_convert(lds, P.w_gate + (size_t)2048 * 2048, WG1, 2048, 2048, G, bid);
;     }
.Ldyn7_top:
	s_waitcnt lgkmcnt(0)
	s_barrier
	s_add_u32 s10, s54, 0xa000
	s_addc_u32 s11, s55, 0
	s_and_saveexec_b64 s[18:19], s[12:13]
	s_cbranch_execz .Ldyn7_nofetch
	s_waitcnt vmcnt(4)
	ds_write_b32 v46, v47
	s_waitcnt lgkmcnt(0)
.Ldyn7_nofetch:
	s_or_b64 exec, exec, s[18:19]
	s_waitcnt lgkmcnt(0)
	s_barrier
	ds_read_b32 v1, v46
	s_waitcnt lgkmcnt(0)
	v_readfirstlane_b32 s99, v1
	s_and_b32 s99, s99, 0xff
	s_and_b32 s101, s99, 1
	s_lshr_b32 s99, s99, 1
	s_lshr_b32 s4, s99, 4
	s_and_b32 s5, s99, 15
	s_mov_b32 s100, 6
	s_mov_b32 s99, 0
	s_cmp_lt_u32 s4, 1
	s_cbranch_scc1 .Lrk7_done
	s_mov_b32 s100, 5
	s_movk_i32 s99, 96
	s_cmp_lt_u32 s4, 2
	s_cbranch_scc1 .Lrk7_done
	s_mov_b32 s100, 5
	s_movk_i32 s99, 176
	s_cmp_lt_u32 s4, 3
	s_cbranch_scc1 .Lrk7_done
	s_mov_b32 s100, 4
	s_movk_i32 s99, 256
	s_cmp_lt_u32 s4, 4
	s_cbranch_scc1 .Lrk7_done
	s_mov_b32 s100, 4
	s_movk_i32 s99, 320
	s_cmp_lt_u32 s4, 5
	s_cbranch_scc1 .Lrk7_done
	s_mov_b32 s100, 3
	s_movk_i32 s99, 384
	s_cmp_lt_u32 s4, 6
	s_cbranch_scc1 .Lrk7_done
	s_mov_b32 s100, 3
	s_movk_i32 s99, 432
	s_cmp_lt_u32 s4, 7
	s_cbranch_scc1 .Lrk7_done
	s_mov_b32 s100, 2
	s_movk_i32 s99, 480
.Lrk7_done:
	s_mul_i32 s5, s5, s100
	s_add_i32 s99, s99, s5
	s_add_i32 s100, s99, s100
	s_nop 3
	s_cmp_gt_u32 s99, 0x1ff
	s_cbranch_scc1 .Ldyn7_exit
	s_cmpk_lt_i32 s99, 0x200
	s_cselect_b64 s[4:5], -1, 0
	s_cmp_lg_u32 s101, 0
	v_lshl_add_u32 v20, v214, 2, 0
	s_cbranch_scc1 .Ldyn7_call2pre
	s_add_u32 s6, s44, 0x1000000
	s_addc_u32 s7, s45, 0
	s_ashr_i32 s8, s99, 31
	s_lshr_b32 s8, s8, 27
	s_add_i32 s8, s99, s8
	s_lshl_b32 s9, s8, 2
	s_and_b32 s8, s8, 0x3ffffe0
	s_sub_i32 s8, s99, s8
	s_and_b32 s9, s9, 0xffffff80
	s_lshl_b32 s8, s8, 6
	s_waitcnt vmcnt(1)
	v_or_b32_e32 v8, s9, v214
	s_ashr_i32 s9, s8, 31
	s_lshl_b64 s[8:9], s[8:9], 2
	v_and_b32_e32 v24, 15, v164
	s_add_u32 s8, s6, s8
	s_addc_u32 s9, s7, s9
	v_lshlrev_b32_e32 v18, 4, v24
	v_mov_b32_e32 v19, 0
	v_ashrrev_i32_e32 v9, 31, v8
	v_lshl_add_u64 v[10:11], s[8:9], 0, v[18:19]
	v_lshlrev_b64 v[0:1], 13, v[8:9]
	v_lshl_add_u64 v[12:13], v[10:11], 0, v[0:1]
	s_mov_b32 s10, 0x40000
	v_or_b32_e32 v8, 64, v8
	v_add_co_u32_e32 v14, vcc, s10, v12
	v_ashrrev_i32_e32 v9, 31, v8
	s_nop 0
	v_addc_co_u32_e32 v15, vcc, 0, v13, vcc
	v_lshlrev_b64 v[8:9], 13, v[8:9]
	s_mov_b32 s11, 0xc0000
	v_lshl_add_u64 v[16:17], v[10:11], 0, v[8:9]
	v_add_co_u32_e32 v22, vcc, s11, v12
	global_load_dwordx4 v[0:3], v[12:13], off nt
	global_load_dwordx4 v[4:7], v[14:15], off nt
	v_addc_co_u32_e32 v23, vcc, 0, v13, vcc
	global_load_dwordx4 v[8:11], v[16:17], off nt
	global_load_dwordx4 v[12:15], v[22:23], off nt
	v_add_u32_e32 v21, 0x200, v164
	v_add_u32_e32 v22, 0, v18
	v_lshrrev_b32_e32 v21, 4, v21
	v_mul_u32_u24_e32 v23, 0x104, v214
	v_lshl_add_u32 v27, v21, 2, 0
	v_mul_u32_u24_e32 v28, 0x820, v24
	v_add_u32_e32 v22, v22, v23
	v_lshl_add_u64 v[16:17], s[6:7], 0, v[18:19]
	v_lshl_add_u64 v[18:19], s[24:25], 0, v[18:19]
	s_lshl_b32 s17, s99, 6
	s_lshl_b32 s16, s98, 6
	v_add_u32_e32 v23, 0x2080, v22
	v_add_u32_e32 v24, 0x2088, v22
	v_add_u32_e32 v25, 0x4100, v22
	v_add_u32_e32 v26, v20, v28
	v_add_u32_e32 v27, v27, v28
	v_add_u32_e32 v28, 0x4108, v22
	v_add_u32_e32 v29, 0x6180, v22
	s_mov_b32 s18, s99
	s_branch .LBB0_625

; template <bool REMAP = false>
; __device__ __forceinline__ void transpose_convert(LAS unsigned char* lds, const float* src, bf16_t* dst, int K, int N, int G, int bid) {
;     ...
;     for (int t = bid; t < ntiles; t += G) {
;         const int k0 = (t / ntn) * 128, n0 = (t % ntn) * 64;
;         asm volatile("s_waitcnt lgkmcnt(0)" ::: "memory"); __builtin_amdgcn_s_barrier(); asm volatile("" ::: "memory");
; #pragma unroll
;         for (int i = 0; i < 4; ++i) {
; #pragma unroll
;             for (int j = 0; j < 4; ++j) tile[(r0 + 32 * i) * 65 + c4 * 4 + j] = v[i][j]; }
;         asm volatile("s_waitcnt lgkmcnt(0)" ::: "memory"); __builtin_amdgcn_s_barrier(); asm volatile("" ::: "memory");
;         if (t + G < ntiles) { const int k1 = ((t + G) / ntn) * 128, n1 = ((t + G) % ntn) * 64;
.LBB0_625:
	s_nop 0
	v_add_u32_e32 v30, 0x6188, v22
	s_waitcnt lgkmcnt(0)
	s_barrier
	s_waitcnt vmcnt(3)
	ds_write2_b32 v22, v0, v1 offset1:1
	ds_write2_b32 v22, v2, v3 offset0:2 offset1:3
	s_waitcnt vmcnt(2)
	ds_write2_b32 v23, v4, v5 offset1:1
	ds_write2_b32 v24, v6, v7 offset1:1
	s_waitcnt vmcnt(1)
	ds_write2_b32 v25, v8, v9 offset1:1
	ds_write2_b32 v28, v10, v11 offset1:1
	s_waitcnt vmcnt(0)
	ds_write2_b32 v29, v12, v13 offset1:1
	ds_write2_b32 v30, v14, v15 offset1:1
	s_waitcnt lgkmcnt(0)
	s_barrier
	s_add_i32 s19, s18, s98
	s_cmp_ge_i32 s19, s100
	s_cselect_b64 s[6:7], -1, 0
	s_cmp_lt_i32 s19, s100
	s_mov_b64 s[8:9], -1
	s_cbranch_scc1 .LBB0_627
	s_add_i32 s28, s17, s16
	s_mov_b64 s[8:9], 0

; #define LAS __attribute__((address_space(3)))
; template <bool REMAP = false>
; __device__ __forceinline__ void transpose_convert(LAS unsigned char* lds, const float* src, bf16_t* dst, int K, int N, int G, int bid) {
;     LAS float* tile = (LAS float*)lds;
;     const int tid = threadIdx.x, ntn = N / 64, ntiles = (K / 128) * ntn;
;     const int r0 = tid >> 4, c4 = tid & 15;
;     f32x4 v[4];
;     if (bid < ntiles) { const int k0 = (bid / ntn) * 128, n0 = (bid % ntn) * 64;
; #pragma unroll
;         for (int i = 0; i < 4; ++i) v[i] = __builtin_nontemporal_load((const f32x4*)(src + (size_t)(k0 + r0 + 32 * i) * N + n0 + c4 * 4)); }
; __global__ void __launch_bounds__(NTHREADS, 2) mk_fwd(Params P) {
;     ...
;         transpose_convert(lds, P.w_gate + (size_t)2048 * 2048, WG1, 2048, 2048, G, bid);
.Ldyn7_call2pre:
	s_add_u32 s4, s50, 0x1000000
	s_addc_u32 s5, s51, 0
	s_ashr_i32 s6, s99, 31
	s_lshr_b32 s6, s6, 27
	s_add_i32 s6, s99, s6
	s_lshl_b32 s7, s6, 2
	s_and_b32 s6, s6, 0x3ffffe0
	s_sub_i32 s6, s99, s6
	s_and_b32 s7, s7, 0xffffff80
	s_lshl_b32 s6, s6, 6
	v_or_b32_e32 v8, s7, v214
	s_ashr_i32 s7, s6, 31
	s_lshl_b64 s[6:7], s[6:7], 2
	v_and_b32_e32 v24, 15, v164
	s_add_u32 s6, s4, s6
	s_addc_u32 s7, s5, s7
	v_lshlrev_b32_e32 v18, 4, v24
	v_mov_b32_e32 v19, 0
	v_ashrrev_i32_e32 v9, 31, v8
	v_lshl_add_u64 v[10:11], s[6:7], 0, v[18:19]
	v_lshlrev_b64 v[0:1], 13, v[8:9]
	v_lshl_add_u64 v[12:13], v[10:11], 0, v[0:1]
	s_mov_b32 s8, 0x40000
	v_or_b32_e32 v8, 64, v8
	v_add_co_u32_e32 v14, vcc, s8, v12
	v_ashrrev_i32_e32 v9, 31, v8
	s_nop 0
	v_addc_co_u32_e32 v15, vcc, 0, v13, vcc
	v_lshlrev_b64 v[8:9], 13, v[8:9]
	s_mov_b32 s9, 0xc0000
	v_lshl_add_u64 v[16:17], v[10:11], 0, v[8:9]
	v_add_co_u32_e32 v22, vcc, s9, v12
	global_load_dwordx4 v[0:3], v[12:13], off nt
	global_load_dwordx4 v[4:7], v[14:15], off nt
	v_addc_co_u32_e32 v23, vcc, 0, v13, vcc
	global_load_dwordx4 v[8:11], v[16:17], off nt
	global_load_dwordx4 v[12:15], v[22:23], off nt
	v_add_u32_e32 v21, 0x200, v164
	v_add_u32_e32 v22, 0, v18
	v_lshrrev_b32_e32 v21, 4, v21
	v_mul_u32_u24_e32 v23, 0x104, v214
	v_lshl_add_u32 v26, v21, 2, 0
	v_mul_u32_u24_e32 v27, 0x820, v24
	v_add_u32_e32 v22, v22, v23
	v_lshl_add_u64 v[16:17], s[4:5], 0, v[18:19]
	v_lshl_add_u64 v[18:19], s[22:23], 0, v[18:19]
	s_lshl_b32 s11, s99, 6
	s_lshl_b32 s10, s98, 6
	v_add_u32_e32 v23, 0x2080, v22
	v_add_u32_e32 v24, 0x2088, v22
	v_add_u32_e32 v25, 0x4100, v22
	v_add_u32_e32 v20, v20, v27
	v_add_u32_e32 v26, v26, v27
	v_add_u32_e32 v27, 0x4108, v22
	v_add_u32_e32 v28, 0x6180, v22
	s_mov_b32 s16, s99
	s_branch .LBB0_632

; template <bool REMAP = false>
; __device__ __forceinline__ void transpose_convert(LAS unsigned char* lds, const float* src, bf16_t* dst, int K, int N, int G, int bid) {
;     ...
;     for (int t = bid; t < ntiles; t += G) {
;         const int k0 = (t / ntn) * 128, n0 = (t % ntn) * 64;
;         asm volatile("s_waitcnt lgkmcnt(0)" ::: "memory"); __builtin_amdgcn_s_barrier(); asm volatile("" ::: "memory");
; #pragma unroll
;         for (int i = 0; i < 4; ++i) {
; #pragma unroll
;             for (int j = 0; j < 4; ++j) tile[(r0 + 32 * i) * 65 + c4 * 4 + j] = v[i][j]; }
;         asm volatile("s_waitcnt lgkmcnt(0)" ::: "memory"); __builtin_amdgcn_s_barrier(); asm volatile("" ::: "memory");
;         if (t + G < ntiles) { const int k1 = ((t + G) / ntn) * 128, n1 = ((t + G) % ntn) * 64;
.LBB0_632:
	v_add_u32_e32 v29, 0x6188, v22
	s_waitcnt lgkmcnt(0)
	s_barrier
	s_waitcnt vmcnt(3)
	ds_write2_b32 v22, v0, v1 offset1:1
	ds_write2_b32 v22, v2, v3 offset0:2 offset1:3
	s_waitcnt vmcnt(2)
	ds_write2_b32 v23, v4, v5 offset1:1
	ds_write2_b32 v24, v6, v7 offset1:1
	s_waitcnt vmcnt(1)
	ds_write2_b32 v25, v8, v9 offset1:1
	ds_write2_b32 v27, v10, v11 offset1:1
	s_waitcnt vmcnt(0)
	ds_write2_b32 v28, v12, v13 offset1:1
	ds_write2_b32 v29, v14, v15 offset1:1
	s_waitcnt lgkmcnt(0)
	s_barrier
	s_add_i32 s17, s16, s98
	s_cmp_ge_i32 s17, s100
	s_cselect_b64 s[4:5], -1, 0
	s_cmp_lt_i32 s17, s100
	s_mov_b64 s[6:7], -1
	s_cbranch_scc1 .LBB0_634
	s_add_i32 s18, s11, s10
	s_mov_b64 s[6:7], 0

; __global__ void __launch_bounds__(NTHREADS, 2) mk_fwd(Params P) {
;     ...
;     if (IN(7)) {
;         transpose_convert(lds, P.w_out + (size_t)2048 * 2048, WOUT1, 2048, 2048, G, bid);
;         transpose_convert(lds, P.w_gate + (size_t)2048 * 2048, WG1, 2048, 2048, G, bid);
;     }
;     if (IN(7)) attn_phase(lds, Qb, Kb, VTb, Zb, KPART, Y1, G, bid);
.Ldyn7_exit:
	v_readlane_b32 s16, v254, 8
	v_readlane_b32 s17, v254, 9
